# MLA attention row sums: 8 two-pass v_mfma_f32_4x4x4_16b_bf16 per tile instead of 4 eight-pass ones-fragment 32x32x16 MFMAs
# baseline (speedup 1.0000x reference)
; DI float bflo(unsigned u) { return __uint_as_float(u << 16); }
; DI float bfhi(unsigned u) { return __uint_as_float(u & 0xffff0000u); }
; DI float shx(float v, int m, int lane) { return __int_as_float(__builtin_amdgcn_ds_bpermute((lane ^ m) << 2, __float_as_int(v))); }
; template <int KW, int DQK, int DV, int MODE> ...
;     ...
;         for (int t = 1; t < NT; ++t) AD_STEP(true, (void)0);
;     }
;     ...
;     rowsum_pw(pw, ls);
;     pv_tile<DV, VP>(o, pw, lds + ((NT - 1) & 1) * VT + voff);
;     l = (ls[0] + ls[1]) + (ls[2] + ls[3]);
;     __syncthreads();
;     ...
;     l += shx(l, 32, lane);
;     if (MODE == 0) l += __int_as_float(__builtin_amdgcn_ds_bpermute((lane & 31) << 2, __float_as_int(osum[0])));
;     l_out = l;
; DI void store_y64(const f32x16 (&o)[2], float linv, bf16_t* Y, const bf16_t* proj, int token, int ycol, int hi) {
; #pragma unroll
;     for (int d0 = 0; d0 < 2; ++d0)
; #pragma unroll
;         for (int g = 0; g < 4; ++g) {
;             const int col = ycol + 32 * d0 + 8 * g + 4 * hi;
;             const u32x2 gv = *(const u32x2*)(proj + (size_t)token * LDP + C_SILU + col);
;             u32x2 w;
;             w.x = cvt_pk(o[d0][4 * g + 0] * linv * bflo(gv.x), o[d0][4 * g + 1] * linv * bfhi(gv.x));
;             w.y = cvt_pk(o[d0][4 * g + 2] * linv * bflo(gv.y), o[d0][4 * g + 3] * linv * bfhi(gv.y));
;             *(u32x2*)(Y + (size_t)token * DM + col) = w;
;         }
.LBB0_624:
	s_or_b64 exec, exec, s[6:7]
	v_exp_f32_e32 v48, v48
	v_exp_f32_e32 v49, v49
	v_exp_f32_e32 v50, v50
	v_exp_f32_e32 v51, v51
	v_exp_f32_e32 v52, v52
	v_exp_f32_e32 v53, v53
	v_cvt_pk_bf16_f32 v48, v48, v49
	v_cvt_pk_bf16_f32 v49, v50, v51
	v_exp_f32_e32 v51, v54
	v_cvt_pk_bf16_f32 v50, v52, v53
	v_exp_f32_e32 v52, v55
	v_exp_f32_e32 v53, v88
	v_exp_f32_e32 v54, v89
	v_exp_f32_e32 v55, v90
	v_exp_f32_e32 v88, v91
	v_exp_f32_e32 v89, v92
	v_exp_f32_e32 v90, v93
	v_mov_b32_e32 v92, v252
	s_mov_b32 s6, s20
	v_cvt_pk_bf16_f32 v51, v51, v52
	v_cvt_pk_bf16_f32 v52, v53, v54
	v_cvt_pk_bf16_f32 v53, v55, v88
	v_cvt_pk_bf16_f32 v54, v89, v90
	v_exp_f32_e32 v55, v80
	v_exp_f32_e32 v127, v81
	v_exp_f32_e32 v154, v82
	v_exp_f32_e32 v155, v83
	s_waitcnt vmcnt(0)
	ds_write_b128 v197, v[146:149] offset:38912
	s_waitcnt lgkmcnt(0)
	s_barrier
	ds_read_b64_tr_b16 v[122:123], v198 offset:38912
	ds_read_b64_tr_b16 v[124:125], v198 offset:40448
	ds_read_b64_tr_b16 v[132:133], v198 offset:40512
	ds_read_b64_tr_b16 v[130:131], v198 offset:38976
	ds_read_b64_tr_b16 v[134:135], v198 offset:41984
	ds_read_b64_tr_b16 v[136:137], v198 offset:43520
	ds_read_b64_tr_b16 v[118:119], v198 offset:43584
	ds_read_b64_tr_b16 v[116:117], v198 offset:42048
	ds_read_b64_tr_b16 v[138:139], v198 offset:45056
	ds_read_b64_tr_b16 v[140:141], v198 offset:46592
	ds_read_b64_tr_b16 v[90:91], v198 offset:46656
	ds_read_b64_tr_b16 v[88:89], v198 offset:45120
	ds_read_b64_tr_b16 v[142:143], v198 offset:48128
	ds_read_b64_tr_b16 v[144:145], v198 offset:49664
	ds_read_b64_tr_b16 v[82:83], v198 offset:49728
	ds_read_b64_tr_b16 v[80:81], v198 offset:48192
	s_waitcnt lgkmcnt(0)
	s_barrier
	s_lshl_b32 s7, s6, 8
	s_and_b32 s7, s7, 0x1f00
	s_add_i32 s7, s7, s30
	v_and_or_b32 v126, v92, 31, s7
	s_lshl_b32 s6, s6, 1
	v_ashrrev_i32_e32 v92, 3, v92
	s_andn2_b32 s6, s6, 63
	v_and_b32_e32 v92, -4, v92
	v_add_u32_e32 v92, s6, v92
	v_mov_b64_e32 v[120:121], s[2:3]
	v_mad_i64_i32 v[120:121], s[6:7], v126, s68, v[120:121]
	v_ashrrev_i32_e32 v93, 31, v92
	v_lshl_add_u64 v[120:121], v[120:121], 0, s[88:89]
	v_lshlrev_b64 v[150:151], 1, v[92:93]
	v_lshl_add_u64 v[146:147], v[120:121], 0, v[150:151]
	global_load_dwordx2 v[152:153], v[146:147], off
	global_load_dwordx2 v[156:157], v[146:147], off offset:16
	global_load_dwordx2 v[158:159], v[146:147], off offset:32
	global_load_dwordx2 v[160:161], v[146:147], off offset:48
	global_load_dwordx2 v[162:163], v[146:147], off offset:64
	global_load_dwordx2 v[164:165], v[146:147], off offset:80
	global_load_dwordx2 v[166:167], v[146:147], off offset:96
	global_load_dwordx2 v[168:169], v[146:147], off offset:112
	v_mfma_f32_4x4x4_16b_bf16 v[112:115], v[66:67], v[108:109], v[112:115]
	s_nop 1
	v_mfma_f32_4x4x4_16b_bf16 v[112:115], v[66:67], v[110:111], v[112:115]
	v_cvt_pk_bf16_f32 v146, v55, v127
	v_exp_f32_e32 v55, v84
	v_exp_f32_e32 v84, v85
	v_exp_f32_e32 v56, v56
	v_exp_f32_e32 v57, v57
	v_exp_f32_e32 v62, v62
	v_cvt_pk_bf16_f32 v148, v55, v84
	v_mfma_f32_4x4x4_16b_bf16 v[112:115], v[66:67], v[104:105], v[112:115]
	s_nop 1
	v_mfma_f32_4x4x4_16b_bf16 v[112:115], v[66:67], v[106:107], v[112:115]
	v_cvt_pk_bf16_f32 v104, v56, v57
	v_exp_f32_e32 v55, v60
	v_exp_f32_e32 v57, v86
	v_exp_f32_e32 v60, v87
	v_exp_f32_e32 v63, v63
	v_cvt_pk_bf16_f32 v147, v154, v155
	v_exp_f32_e32 v56, v61
	v_mfma_f32_4x4x4_16b_bf16 v[112:115], v[66:67], v[100:101], v[112:115]
	s_nop 1
	v_mfma_f32_4x4x4_16b_bf16 v[112:115], v[66:67], v[102:103], v[112:115]
	v_cvt_pk_bf16_f32 v149, v57, v60
	v_exp_f32_e32 v58, v58
	v_exp_f32_e32 v59, v59
	v_cvt_pk_bf16_f32 v107, v62, v63
	v_exp_f32_e32 v61, v94
	v_exp_f32_e32 v62, v95
	v_cvt_pk_bf16_f32 v106, v55, v56
	v_mfma_f32_32x32x16_bf16 v[32:47], v[122:125], v[146:149], v[32:47]
	v_cvt_pk_bf16_f32 v105, v58, v59
	v_mov_b32_e32 v56, v112
	v_mov_b32_e32 v58, v129
	v_mov_b32_e32 v57, v129
	v_mov_b32_e32 v59, v129
	v_cvt_pk_bf16_f32 v55, v61, v62
	v_dot2c_f32_bf16_e32 v56, 0x3f803f80, v146
	v_dot2c_f32_bf16_e32 v56, 0x3f803f80, v96
	v_dot2c_f32_bf16_e32 v58, 0x3f803f80, v97
	v_dot2c_f32_bf16_e32 v57, 0x3f803f80, v98
	v_dot2c_f32_bf16_e32 v59, 0x3f803f80, v99
	v_dot2c_f32_bf16_e32 v58, 0x3f803f80, v147
	v_dot2c_f32_bf16_e32 v57, 0x3f803f80, v148
	v_dot2c_f32_bf16_e32 v59, 0x3f803f80, v149
	v_dot2c_f32_bf16_e32 v56, 0x3f803f80, v52
	v_dot2c_f32_bf16_e32 v58, 0x3f803f80, v53
	v_dot2c_f32_bf16_e32 v57, 0x3f803f80, v54
	v_dot2c_f32_bf16_e32 v59, 0x3f803f80, v55
	v_dot2c_f32_bf16_e32 v56, 0x3f803f80, v48
	v_dot2c_f32_bf16_e32 v58, 0x3f803f80, v49
	v_dot2c_f32_bf16_e32 v57, 0x3f803f80, v50
	v_dot2c_f32_bf16_e32 v59, 0x3f803f80, v51
	v_mfma_f32_32x32x16_bf16 v[32:47], v[134:137], v[52:55], v[32:47]
	v_dot2c_f32_bf16_e32 v56, 0x3f803f80, v104
	v_dot2c_f32_bf16_e32 v58, 0x3f803f80, v105
	v_dot2c_f32_bf16_e32 v57, 0x3f803f80, v106
	v_dot2c_f32_bf16_e32 v59, 0x3f803f80, v107
	v_ashrrev_i32_e32 v127, 31, v126
	s_add_i32 s20, s20, s28
	s_cmpk_gt_i32 s20, 0xff
	v_pk_add_f32 v[56:57], v[56:57], v[58:59]
	ds_bpermute_b32 v58, v200, v64
	v_add_f32_e32 v56, v56, v57
	ds_bpermute_b32 v57, v199, v56
	v_mfma_f32_32x32x16_bf16 v[32:47], v[138:141], v[48:51], v[32:47]
	s_waitcnt lgkmcnt(0)
; #define LAS __attribute__((address_space(3)))
; DI float bflo(unsigned u) { return __uint_as_float(u << 16); }
; DI float bfhi(unsigned u) { return __uint_as_float(u & 0xffff0000u); }
; #define MFMA32(a, b, c) __builtin_amdgcn_mfma_f32_32x32x16_bf16((a), (b), (c), 0, 0, 0)
; DI s16x4 vtr(const LAS unsigned char* p) { return __builtin_bit_cast(s16x4, __builtin_amdgcn_ds_read_tr16_b64_v4i16((LAS v4i16_t*)p)); }
; template <int DV, int VP>
; DI void pv_tile(f32x16 (&o)[DV / 32], const u32x4 (&pw)[4], const LAS unsigned char* vp) {
; #pragma unroll
;     for (int kh = 0; kh < 2; ++kh) {
;         bf16x8 vf[DV / 32][2];
; #pragma unroll
;         for (int d0 = 0; d0 < DV / 32; ++d0)
; #pragma unroll
;             for (int k2 = 0; k2 < 2; ++k2) { const int ks = 2 * kh + k2;
;                 const s16x4 lo = vtr(vp + (16 * ks) * VP + d0 * 64);
;                 const s16x4 hh = vtr(vp + (16 * ks + 8) * VP + d0 * 64);
;                 vf[d0][k2] = (bf16x8){lo[0], lo[1], lo[2], lo[3], hh[0], hh[1], hh[2], hh[3]}; }
; #pragma unroll
;         for (int k2 = 0; k2 < 2; ++k2)
; #pragma unroll
;             for (int d0 = 0; d0 < DV / 32; ++d0) o[d0] = MFMA32(vf[d0][k2], __builtin_bit_cast(bf16x8, pw[2 * kh + k2]), o[d0]);
;     }
; }
; DI void store_y64(const f32x16 (&o)[2], float linv, bf16_t* Y, const bf16_t* proj, int token, int ycol, int hi) {
; #pragma unroll
;     for (int d0 = 0; d0 < 2; ++d0)
; #pragma unroll
;         for (int g = 0; g < 4; ++g) {
;             const int col = ycol + 32 * d0 + 8 * g + 4 * hi;
;             const u32x2 gv = *(const u32x2*)(proj + (size_t)token * LDP + C_SILU + col);
;             u32x2 w;
;             w.x = cvt_pk(o[d0][4 * g + 0] * linv * bflo(gv.x), o[d0][4 * g + 1] * linv * bfhi(gv.x));
;             w.y = cvt_pk(o[d0][4 * g + 2] * linv * bflo(gv.y), o[d0][4 * g + 3] * linv * bfhi(gv.y));
;             *(u32x2*)(Y + (size_t)token * DM + col) = w;
;         }
	v_add_f32_e32 v56, v56, v57
	v_add_f32_e32 v56, v56, v58
	v_div_scale_f32 v57, s[6:7], v56, v56, 1.0
	v_rcp_f32_e32 v58, v57
	v_mfma_f32_32x32x16_bf16 v[32:47], v[142:145], v[104:107], v[32:47]
	v_fma_f32 v59, -v57, v58, 1.0
	v_fmac_f32_e32 v58, v59, v58
	v_div_scale_f32 v59, vcc, 1.0, v56, 1.0
	v_mul_f32_e32 v60, v59, v58
	v_fma_f32 v61, -v57, v60, v59
	v_fmac_f32_e32 v60, v61, v58
	v_fma_f32 v57, -v57, v60, v59
	v_div_fmas_f32 v57, v57, v58, v60
	v_div_fixup_f32 v56, v57, v56, 1.0
	s_nop 2
	v_pk_mul_f32 v[32:33], v[32:33], v[56:57] op_sel_hi:[1,0]
	s_waitcnt vmcnt(7)
	v_lshlrev_b32_e32 v60, 16, v152
	v_and_b32_e32 v61, 0xffff0000, v152
	v_pk_mul_f32 v[32:33], v[32:33], v[60:61]
	v_lshlrev_b64 v[58:59], 12, v[126:127]
	v_cvt_pk_bf16_f32 v60, v32, v33
	v_pk_mul_f32 v[32:33], v[34:35], v[56:57] op_sel_hi:[1,0]
	v_lshlrev_b32_e32 v34, 16, v153
	v_and_b32_e32 v35, 0xffff0000, v153
	v_lshl_add_u64 v[58:59], s[4:5], 0, v[58:59]
	v_pk_mul_f32 v[32:33], v[32:33], v[34:35]
	v_add_u32_e32 v34, 8, v92
	v_cvt_pk_bf16_f32 v61, v32, v33
	v_lshl_add_u64 v[32:33], v[58:59], 0, v[150:151]
	v_ashrrev_i32_e32 v35, 31, v34
	global_store_dwordx2 v[32:33], v[60:61], off
	v_lshl_add_u64 v[34:35], v[34:35], 1, v[120:121]
	v_pk_mul_f32 v[36:37], v[36:37], v[56:57] op_sel_hi:[1,0]
	v_pk_mul_f32 v[38:39], v[38:39], v[56:57] op_sel_hi:[1,0]
	v_add_u32_e32 v58, 16, v92
	v_ashrrev_i32_e32 v59, 31, v58
	v_lshl_add_u64 v[58:59], v[58:59], 1, v[120:121]
	v_mfma_f32_32x32x16_bf16 v[16:31], v[130:133], v[146:149], v[16:31]
	s_waitcnt vmcnt(7)
	v_lshlrev_b32_e32 v60, 16, v156
	v_and_b32_e32 v61, 0xffff0000, v156
	v_lshlrev_b32_e32 v34, 16, v157
	v_and_b32_e32 v35, 0xffff0000, v157
	v_pk_mul_f32 v[36:37], v[36:37], v[60:61]
	v_pk_mul_f32 v[34:35], v[38:39], v[34:35]
	v_cvt_pk_bf16_f32 v36, v36, v37
	v_cvt_pk_bf16_f32 v37, v34, v35
	global_store_dwordx2 v[32:33], v[36:37], off offset:16
	v_pk_mul_f32 v[38:39], v[40:41], v[56:57] op_sel_hi:[1,0]
	v_pk_mul_f32 v[40:41], v[42:43], v[56:57] op_sel_hi:[1,0]
	v_add_u32_e32 v36, 24, v92
	v_ashrrev_i32_e32 v37, 31, v36
	v_lshl_add_u64 v[36:37], v[36:37], 1, v[120:121]
	v_mfma_f32_32x32x16_bf16 v[16:31], v[116:119], v[52:55], v[16:31]
	s_waitcnt vmcnt(7)
	v_lshlrev_b32_e32 v42, 16, v158
	v_and_b32_e32 v43, 0xffff0000, v158
	v_lshlrev_b32_e32 v34, 16, v159
	v_and_b32_e32 v35, 0xffff0000, v159
	v_pk_mul_f32 v[38:39], v[38:39], v[42:43]
	v_pk_mul_f32 v[34:35], v[40:41], v[34:35]
	v_cvt_pk_bf16_f32 v38, v38, v39
	v_cvt_pk_bf16_f32 v39, v34, v35
	global_store_dwordx2 v[32:33], v[38:39], off offset:32
	v_pk_mul_f32 v[38:39], v[44:45], v[56:57] op_sel_hi:[1,0]
	v_pk_mul_f32 v[40:41], v[46:47], v[56:57] op_sel_hi:[1,0]
	v_add_u32_e32 v36, 32, v92
	v_ashrrev_i32_e32 v37, 31, v36
	v_lshl_add_u64 v[36:37], v[36:37], 1, v[120:121]
	v_mfma_f32_32x32x16_bf16 v[16:31], v[88:91], v[48:51], v[16:31]
	s_waitcnt vmcnt(7)
	v_lshlrev_b32_e32 v42, 16, v160
	v_and_b32_e32 v43, 0xffff0000, v160
	v_lshlrev_b32_e32 v34, 16, v161
	v_and_b32_e32 v35, 0xffff0000, v161
	v_pk_mul_f32 v[38:39], v[38:39], v[42:43]
	v_pk_mul_f32 v[34:35], v[40:41], v[34:35]
	v_cvt_pk_bf16_f32 v38, v38, v39
	v_cvt_pk_bf16_f32 v39, v34, v35
	global_store_dwordx2 v[32:33], v[38:39], off offset:48
	v_mfma_f32_32x32x16_bf16 v[16:31], v[80:83], v[104:107], v[16:31]
	v_add_u32_e32 v36, 40, v92
	v_ashrrev_i32_e32 v37, 31, v36
	v_lshl_add_u64 v[36:37], v[36:37], 1, v[120:121]
	s_waitcnt vmcnt(7)
	v_lshlrev_b32_e32 v38, 16, v162
	s_nop 6
	v_pk_mul_f32 v[16:17], v[16:17], v[56:57] op_sel_hi:[1,0]
	v_pk_mul_f32 v[18:19], v[18:19], v[56:57] op_sel_hi:[1,0]
	v_and_b32_e32 v39, 0xffff0000, v162
	v_lshlrev_b32_e32 v34, 16, v163
	v_and_b32_e32 v35, 0xffff0000, v163
	v_pk_mul_f32 v[16:17], v[16:17], v[38:39]
	v_pk_mul_f32 v[18:19], v[18:19], v[34:35]
	v_cvt_pk_bf16_f32 v16, v16, v17
	v_cvt_pk_bf16_f32 v17, v18, v19
	global_store_dwordx2 v[32:33], v[16:17], off offset:64
	v_pk_mul_f32 v[20:21], v[20:21], v[56:57] op_sel_hi:[1,0]
	v_pk_mul_f32 v[22:23], v[22:23], v[56:57] op_sel_hi:[1,0]
	v_add_u32_e32 v18, 48, v92
	v_ashrrev_i32_e32 v19, 31, v18
	v_lshl_add_u64 v[18:19], v[18:19], 1, v[120:121]
	s_waitcnt vmcnt(7)
	v_lshlrev_b32_e32 v34, 16, v164
	v_and_b32_e32 v35, 0xffff0000, v164
	v_lshlrev_b32_e32 v16, 16, v165
	v_and_b32_e32 v17, 0xffff0000, v165
	v_pk_mul_f32 v[20:21], v[20:21], v[34:35]
	v_pk_mul_f32 v[16:17], v[22:23], v[16:17]
	v_cvt_pk_bf16_f32 v20, v20, v21
	v_cvt_pk_bf16_f32 v21, v16, v17
	global_store_dwordx2 v[32:33], v[20:21], off offset:80
	v_pk_mul_f32 v[20:21], v[24:25], v[56:57] op_sel_hi:[1,0]
	v_pk_mul_f32 v[22:23], v[26:27], v[56:57] op_sel_hi:[1,0]
	v_add_u32_e32 v18, 56, v92
	v_ashrrev_i32_e32 v19, 31, v18
	v_lshl_add_u64 v[18:19], v[18:19], 1, v[120:121]
	s_waitcnt vmcnt(7)
	v_lshlrev_b32_e32 v24, 16, v166
	v_and_b32_e32 v25, 0xffff0000, v166
	v_lshlrev_b32_e32 v16, 16, v167
	v_and_b32_e32 v17, 0xffff0000, v167
	v_pk_mul_f32 v[20:21], v[20:21], v[24:25]
	v_pk_mul_f32 v[16:17], v[22:23], v[16:17]
	v_cvt_pk_bf16_f32 v20, v20, v21
	v_cvt_pk_bf16_f32 v21, v16, v17
	global_store_dwordx2 v[32:33], v[20:21], off offset:96
	v_pk_mul_f32 v[18:19], v[28:29], v[56:57] op_sel_hi:[1,0]
	v_pk_mul_f32 v[20:21], v[30:31], v[56:57] op_sel_hi:[1,0]
	s_waitcnt vmcnt(7)
	v_lshlrev_b32_e32 v22, 16, v168
	v_and_b32_e32 v23, 0xffff0000, v168
	v_lshlrev_b32_e32 v16, 16, v169
	v_and_b32_e32 v17, 0xffff0000, v169
	v_pk_mul_f32 v[18:19], v[18:19], v[22:23]
	v_pk_mul_f32 v[16:17], v[20:21], v[16:17]
	v_cvt_pk_bf16_f32 v18, v18, v19
	v_cvt_pk_bf16_f32 v19, v16, v17
	global_store_dwordx2 v[32:33], v[18:19], off offset:112
	s_cbranch_scc1 .LBB0_643

; #define LAS __attribute__((address_space(3)))
; #define MFMA32(a, b, c) __builtin_amdgcn_mfma_f32_32x32x16_bf16((a), (b), (c), 0, 0, 0)
; #define AD_LSTORE_K(b) do { \
;     _Pragma("unroll") for (int i_ = 0; i_ < KPT; ++i_) { if (i_ + 1 < KPT || kact1) *(LAS u32x4*)(lds + (b) * KT + klo[i_]) = kreg[i_]; } } while (0)
; #define AD_LSTORE_V(b) do { \
;     _Pragma("unroll") for (int i_ = 0; i_ < VPT; ++i_) *(LAS u32x4*)(lds + (b) * VT + vlo[i_]) = vreg[i_]; } while (0)
; template <int DQK, int KP>
; DI void qk_tile(f32x16& p0, f32x16& p1, const LAS unsigned char* kp, const bf16x8* qf) {
; #pragma unroll
;     for (int d0 = 0; d0 < DQK / 16; ++d0) {
;         const bf16x8 a0 = *(const LAS bf16x8*)(kp + d0 * 32);
;         const bf16x8 a1 = *(const LAS bf16x8*)(kp + 32 * KP + d0 * 32);
;         p0 = MFMA32(a0, qf[d0], p0); p1 = MFMA32(a1, qf[d0], p1);
;     }
; template <int KW, int DQK, int DV, int MODE> ...
;     ...
;       _Pragma("unroll") for (int i_ = 0; i_ < KPT; ++i_) { if (i_ + 1 < KPT || kact1) *(LAS u32x4*)(lds + klo[i_]) = kreg0[i_]; } }
;     __syncthreads();
;     u32x4 pw[4];
;     { f32x16 pc0, pc1;
;       AD_CINIT(pc0, pc1, 0);
;       qk_tile<DQK, KP>(pc0, pc1, lds + koff, qf);
;       exp_tile(pc0, pc1);
;       pack_tile(pc0, pc1, pw); }
;     AD_LSTORE_K(1); AD_LSTORE_V(0);
;     __syncthreads();
;     float ls[4] = {0.f, 0.f, 0.f, 0.f};
;     f32x16 osum;
; #pragma unroll
;     for (int r = 0; r < 16; ++r) osum[r] = 0.f;
;     bf16x8 onesf;
; #pragma unroll
;     for (int j = 0; j < 8; ++j) onesf[j] = (r32 == 0) ? (short)0x3f80 : (short)0;
;     f32x16 cvec;
; #pragma unroll
;     for (int r = 0; r < 16; ++r) cvec[r] = nbound;
;     asm volatile("" : "+v"(cvec));
.LBB0_629:
	s_or_b64 exec, exec, s[18:19]
	s_lshl_b64 s[10:11], s[10:11], 20
	v_lshl_add_u64 v[182:183], v[250:251], 0, s[10:11]
	global_load_dwordx4 v[64:67], v[182:183], off
	v_add_u32_e32 v202, 0, v194
	v_add_u32_e32 v201, 0, v195
	s_waitcnt vmcnt(2)
	ds_write_b128 v202, v[20:23]
	s_and_saveexec_b64 s[16:17], s[0:1]
	ds_write_b128 v201, v[16:19]
	s_or_b64 exec, exec, s[16:17]
	s_waitcnt lgkmcnt(0)
	s_barrier
	ds_read_b128 v[16:19], v196
	ds_read_b128 v[72:75], v196 offset:6656
	v_mov_b64_e32 v[48:49], s[48:49]
	v_mov_b64_e32 v[50:51], s[50:51]
	v_mov_b64_e32 v[52:53], s[52:53]
	v_mov_b64_e32 v[54:55], s[54:55]
	v_mov_b64_e32 v[56:57], s[56:57]
	v_mov_b64_e32 v[58:59], s[58:59]
	v_mov_b64_e32 v[60:61], s[60:61]
	v_mov_b64_e32 v[62:63], s[62:63]
	s_waitcnt lgkmcnt(1)
	s_nop 0
	v_mfma_f32_32x32x16_bf16 v[32:47], v[16:19], v[142:145], v[48:63]
	s_waitcnt lgkmcnt(0)
	v_mfma_f32_32x32x16_bf16 v[16:31], v[72:75], v[142:145], v[48:63]
	s_nop 6
	ds_read_b128 v[48:51], v196 offset:32
	s_waitcnt lgkmcnt(0)
	v_mfma_f32_32x32x16_bf16 v[32:47], v[48:51], v[138:141], v[32:47]
	ds_read_b128 v[48:51], v196 offset:6688
	s_waitcnt lgkmcnt(0)
	v_mfma_f32_32x32x16_bf16 v[16:31], v[48:51], v[138:141], v[16:31]
	ds_read_b128 v[48:51], v196 offset:64
	s_waitcnt lgkmcnt(0)
	v_mfma_f32_32x32x16_bf16 v[32:47], v[48:51], v[134:137], v[32:47]
	ds_read_b128 v[48:51], v196 offset:6720
	s_waitcnt lgkmcnt(0)
	v_mfma_f32_32x32x16_bf16 v[16:31], v[48:51], v[134:137], v[16:31]
	ds_read_b128 v[48:51], v196 offset:96
	s_waitcnt lgkmcnt(0)
	v_mfma_f32_32x32x16_bf16 v[32:47], v[48:51], v[130:133], v[32:47]
	ds_read_b128 v[48:51], v196 offset:6752
	s_waitcnt lgkmcnt(0)
	v_mfma_f32_32x32x16_bf16 v[16:31], v[48:51], v[130:133], v[16:31]
	ds_read_b128 v[48:51], v196 offset:128
	s_waitcnt lgkmcnt(0)
	v_mfma_f32_32x32x16_bf16 v[32:47], v[48:51], v[120:123], v[32:47]
	ds_read_b128 v[48:51], v196 offset:6784
	s_waitcnt lgkmcnt(0)
	v_mfma_f32_32x32x16_bf16 v[16:31], v[48:51], v[120:123], v[16:31]
	ds_read_b128 v[48:51], v196 offset:160
	s_waitcnt lgkmcnt(0)
	v_mfma_f32_32x32x16_bf16 v[32:47], v[48:51], v[116:119], v[32:47]
	ds_read_b128 v[48:51], v196 offset:6816
	s_waitcnt vmcnt(1)
	ds_write_b128 v202, v[68:71] offset:13312
	s_waitcnt lgkmcnt(1)
	v_mfma_f32_32x32x16_bf16 v[16:31], v[48:51], v[116:119], v[16:31]
	s_and_saveexec_b64 s[16:17], s[0:1]
	ds_write_b128 v201, v[124:127] offset:13312
	s_or_b64 exec, exec, s[16:17]
	s_nop 3
	v_exp_f32_e32 v32, v32
	v_exp_f32_e32 v33, v33
	v_exp_f32_e32 v34, v34
	v_exp_f32_e32 v35, v35
	v_exp_f32_e32 v36, v36
	v_exp_f32_e32 v37, v37
	v_exp_f32_e32 v38, v38
	v_exp_f32_e32 v39, v39
	v_exp_f32_e32 v40, v40
	v_exp_f32_e32 v41, v41
	v_exp_f32_e32 v42, v42
	v_exp_f32_e32 v43, v43
	v_exp_f32_e32 v44, v44
	v_exp_f32_e32 v45, v45
	v_exp_f32_e32 v46, v46
	v_exp_f32_e32 v47, v47
	v_exp_f32_e32 v16, v16
	v_exp_f32_e32 v17, v17
	v_exp_f32_e32 v18, v18
	v_exp_f32_e32 v19, v19
	v_exp_f32_e32 v20, v20
	v_exp_f32_e32 v21, v21
	v_exp_f32_e32 v22, v22
	v_exp_f32_e32 v23, v23
	v_exp_f32_e32 v24, v24
	v_exp_f32_e32 v25, v25
	v_exp_f32_e32 v26, v26
	v_exp_f32_e32 v27, v27
	v_exp_f32_e32 v28, v28
	v_exp_f32_e32 v29, v29
	v_exp_f32_e32 v30, v30
	v_exp_f32_e32 v31, v31
	v_cvt_pk_bf16_f32 v158, v32, v33
	v_mov_b64_e32 v[62:63], v[14:15]
	v_mov_b32_e32 v32, 0
	v_cvt_pk_bf16_f32 v159, v34, v35
	v_cvt_pk_bf16_f32 v160, v36, v37
	v_cvt_pk_bf16_f32 v161, v38, v39
	v_cvt_pk_bf16_f32 v154, v40, v41
	v_cvt_pk_bf16_f32 v155, v42, v43
	v_cvt_pk_bf16_f32 v156, v44, v45
	v_cvt_pk_bf16_f32 v157, v46, v47
	v_cvt_pk_bf16_f32 v150, v16, v17
	v_cvt_pk_bf16_f32 v151, v18, v19
	v_cvt_pk_bf16_f32 v152, v20, v21
	v_cvt_pk_bf16_f32 v153, v22, v23
	v_cvt_pk_bf16_f32 v146, v24, v25
	v_cvt_pk_bf16_f32 v147, v26, v27
	v_cvt_pk_bf16_f32 v148, v28, v29
	v_cvt_pk_bf16_f32 v149, v30, v31
	s_waitcnt vmcnt(0)
	ds_write_b128 v197, v[64:67] offset:26624
	v_mov_b64_e32 v[60:61], v[12:13]
	v_mov_b64_e32 v[58:59], v[10:11]
	v_mov_b64_e32 v[56:57], v[8:9]
	v_mov_b64_e32 v[54:55], v[6:7]
	v_mov_b64_e32 v[52:53], v[4:5]
	v_mov_b64_e32 v[50:51], v[2:3]
	v_mov_b64_e32 v[48:49], v[0:1]
	v_lshl_add_u64 v[184:185], v[212:213], 0, s[10:11]
	v_lshl_add_u64 v[190:191], v[178:179], 0, s[8:9]
	v_lshl_add_u64 v[192:193], v[180:181], 0, s[8:9]
	s_mov_b32 s10, 2
	v_mov_b32_e32 v33, v32
	v_mov_b32_e32 v34, v32
	v_mov_b32_e32 v35, v32
	v_mov_b32_e32 v36, v32
	v_mov_b32_e32 v37, v32
	v_mov_b32_e32 v38, v32
	v_mov_b32_e32 v39, v32
	v_mov_b32_e32 v40, v32
	v_mov_b32_e32 v41, v32
	v_mov_b32_e32 v42, v32
	v_mov_b32_e32 v43, v32
	v_mov_b32_e32 v44, v32
	v_mov_b32_e32 v45, v32
	v_mov_b32_e32 v46, v32
	v_mov_b32_e32 v47, v32
	v_mov_b32_e32 v16, v32
	v_mov_b32_e32 v17, v32
	v_mov_b32_e32 v18, v32
	v_mov_b32_e32 v19, v32
	v_mov_b32_e32 v20, v32
	v_mov_b32_e32 v21, v32
	v_mov_b32_e32 v22, v32
	v_mov_b32_e32 v23, v32
	v_mov_b32_e32 v24, v32
	v_mov_b32_e32 v25, v32
	v_mov_b32_e32 v26, v32
	v_mov_b32_e32 v27, v32
	v_mov_b32_e32 v28, v32
	v_mov_b32_e32 v29, v32
	v_mov_b32_e32 v30, v32
	v_mov_b32_e32 v31, v32
	v_mov_b32_e32 v64, v32
	v_mov_b32_e32 v65, v32
	v_mov_b32_e32 v66, 0x3f803f80
	v_mov_b32_e32 v67, 0x3f803f80
	v_mov_b32_e32 v68, v32
	v_mov_b32_e32 v69, v32
	v_mov_b32_e32 v70, v32
	v_mov_b32_e32 v71, v32
	v_mov_b32_e32 v72, v32
	v_mov_b32_e32 v73, v32
	v_mov_b32_e32 v74, v32
	v_mov_b32_e32 v75, v32
	v_mov_b32_e32 v76, v32
	v_mov_b32_e32 v77, v32
	v_mov_b32_e32 v78, v32
	v_mov_b32_e32 v79, v32
	v_mov_b32_e32 v112, v32
	v_mov_b32_e32 v113, v32
	v_mov_b32_e32 v114, v32
	v_mov_b32_e32 v115, v32
	s_waitcnt lgkmcnt(0)
	s_barrier
	global_load_dwordx4 v[166:169], v[190:191], off
	s_and_saveexec_b64 s[8:9], s[0:1]
	s_cbranch_execz .LBB0_635

.LBB0_635:
	s_or_b64 exec, exec, s[8:9]
	global_load_dwordx4 v[162:165], v[184:185], off
	s_add_i32 s8, s10, -1
	s_and_b32 s11, s8, 1
	s_mul_i32 s8, s11, 0x3400
	v_add_u32_e32 v174, s8, v196
	ds_read_b128 v[80:83], v174
	ds_read_b128 v[204:207], v174 offset:32
	ds_read_b128 v[208:211], v174 offset:6656
	ds_read_b128 v[214:217], v174 offset:6688
	s_xor_b32 s8, s11, 1
	s_mulk_i32 s8, 0x3000
	v_add_u32_e32 v176, s8, v198
	s_waitcnt lgkmcnt(3)
	v_mfma_f32_32x32x16_bf16 v[96:111], v[80:83], v[142:145], v[48:63]
	v_mfma_f32_4x4x4_16b_bf16 v[112:115], v[66:67], v[158:159], v[112:115]
	ds_read_b128 v[222:225], v174 offset:64
	ds_read_b64_tr_b16 v[226:227], v176 offset:26624
	ds_read_b64_tr_b16 v[228:229], v176 offset:28160
	s_waitcnt lgkmcnt(4)
	v_mfma_f32_32x32x16_bf16 v[80:95], v[208:211], v[142:145], v[48:63]
	v_mfma_f32_4x4x4_16b_bf16 v[112:115], v[66:67], v[160:161], v[112:115]
	ds_read_b128 v[208:211], v174 offset:6720
	ds_read_b64_tr_b16 v[230:231], v176 offset:26688
	ds_read_b64_tr_b16 v[232:233], v176 offset:28224
	v_mfma_f32_32x32x16_bf16 v[96:111], v[204:207], v[138:141], v[96:111]
	v_mfma_f32_4x4x4_16b_bf16 v[112:115], v[66:67], v[154:155], v[112:115]
	ds_read_b128 v[204:207], v174 offset:96
	ds_read_b64_tr_b16 v[234:235], v176 offset:29696
	ds_read_b64_tr_b16 v[236:237], v176 offset:31232
	s_waitcnt lgkmcnt(9)
	v_mfma_f32_32x32x16_bf16 v[80:95], v[214:217], v[138:141], v[80:95]
	v_mfma_f32_4x4x4_16b_bf16 v[112:115], v[66:67], v[156:157], v[112:115]
	ds_read_b128 v[214:217], v174 offset:6752
	ds_read_b64_tr_b16 v[238:239], v176 offset:29760
	ds_read_b64_tr_b16 v[240:241], v176 offset:31296
	s_waitcnt lgkmcnt(11)
	v_mfma_f32_32x32x16_bf16 v[96:111], v[222:225], v[134:137], v[96:111]
	v_mfma_f32_4x4x4_16b_bf16 v[112:115], v[66:67], v[150:151], v[112:115]
	ds_read_b128 v[222:225], v174 offset:128
	ds_read_b64_tr_b16 v[242:243], v176 offset:32768
	ds_read_b64_tr_b16 v[244:245], v176 offset:34304
	s_waitcnt lgkmcnt(11)
	v_mfma_f32_32x32x16_bf16 v[80:95], v[208:211], v[134:137], v[80:95]
	v_mfma_f32_4x4x4_16b_bf16 v[112:115], v[66:67], v[152:153], v[112:115]
	ds_read_b128 v[208:211], v174 offset:6784
	ds_read_b64_tr_b16 v[246:247], v176 offset:32832
	ds_read_b64_tr_b16 v[248:249], v176 offset:34368
	s_waitcnt lgkmcnt(11)
	v_mfma_f32_32x32x16_bf16 v[96:111], v[204:207], v[130:133], v[96:111]
	v_mfma_f32_4x4x4_16b_bf16 v[112:115], v[66:67], v[146:147], v[112:115]
	ds_read_b128 v[204:207], v174 offset:160
	ds_read_b64_tr_b16 v[186:187], v176 offset:35840
	ds_read_b64_tr_b16 v[188:189], v176 offset:37376
	s_waitcnt lgkmcnt(11)
	v_mfma_f32_32x32x16_bf16 v[80:95], v[214:217], v[130:133], v[80:95]
	v_mfma_f32_4x4x4_16b_bf16 v[112:115], v[66:67], v[148:149], v[112:115]
	ds_read_b128 v[214:217], v174 offset:6816
	ds_read_b64_tr_b16 v[174:175], v176 offset:35904
	ds_read_b64_tr_b16 v[176:177], v176 offset:37440
	s_waitcnt lgkmcnt(11)
	v_mfma_f32_32x32x16_bf16 v[96:111], v[222:225], v[120:123], v[96:111]
	s_waitcnt lgkmcnt(8)
	v_mfma_f32_32x32x16_bf16 v[80:95], v[208:211], v[120:123], v[80:95]
	s_waitcnt lgkmcnt(5)
	v_mfma_f32_32x32x16_bf16 v[96:111], v[204:207], v[116:119], v[96:111]
	s_waitcnt lgkmcnt(2)
	v_mfma_f32_32x32x16_bf16 v[80:95], v[214:217], v[116:119], v[80:95]
	v_mfma_f32_32x32x16_bf16 v[32:47], v[226:229], v[158:161], v[32:47]
	v_mfma_f32_32x32x16_bf16 v[16:31], v[230:233], v[158:161], v[16:31]
	v_mfma_f32_32x32x16_bf16 v[32:47], v[234:237], v[154:157], v[32:47]
	v_mfma_f32_32x32x16_bf16 v[16:31], v[238:241], v[154:157], v[16:31]
	v_mfma_f32_32x32x16_bf16 v[32:47], v[242:245], v[150:153], v[32:47]
	v_mfma_f32_32x32x16_bf16 v[16:31], v[246:249], v[150:153], v[16:31]
	v_mfma_f32_32x32x16_bf16 v[32:47], v[186:189], v[146:149], v[32:47]
	s_waitcnt lgkmcnt(0)
	v_mfma_f32_32x32x16_bf16 v[16:31], v[174:177], v[146:149], v[16:31]
	s_bitcmp1_b32 s10, 0
	s_cselect_b32 s8, 0x3400, 0
	s_add_i32 s16, s8, 0
	v_add_u32_e32 v174, s16, v194
	s_waitcnt vmcnt(1)
	ds_write_b128 v174, v[166:169]
	s_and_saveexec_b64 s[8:9], s[0:1]
	v_add_u32_e32 v166, s16, v195
	ds_write_b128 v166, v[124:127]
	s_or_b64 exec, exec, s[8:9]
	v_exp_f32_e32 v166, v96
	v_exp_f32_e32 v167, v97
	v_exp_f32_e32 v98, v98
	v_exp_f32_e32 v99, v99
	v_exp_f32_e32 v168, v100
	v_exp_f32_e32 v169, v101
	v_exp_f32_e32 v174, v102
	v_exp_f32_e32 v175, v103
	v_exp_f32_e32 v104, v104
	v_exp_f32_e32 v176, v105
	v_exp_f32_e32 v105, v106
	v_exp_f32_e32 v177, v107
	v_exp_f32_e32 v106, v108
	v_exp_f32_e32 v108, v109
	v_exp_f32_e32 v107, v110
	v_exp_f32_e32 v109, v111
	v_exp_f32_e32 v80, v80
	v_exp_f32_e32 v81, v81
	v_exp_f32_e32 v82, v82
	v_exp_f32_e32 v83, v83
	v_exp_f32_e32 v84, v84
	v_exp_f32_e32 v85, v85
	v_exp_f32_e32 v86, v86
	v_exp_f32_e32 v87, v87
	v_exp_f32_e32 v88, v88
	v_exp_f32_e32 v89, v89
	v_exp_f32_e32 v90, v90
	v_exp_f32_e32 v91, v91
	v_exp_f32_e32 v92, v92
	v_exp_f32_e32 v93, v93
	v_exp_f32_e32 v94, v94
	v_exp_f32_e32 v95, v95
	s_mulk_i32 s11, 0x3000
	s_add_i32 s10, s10, 1
	s_mov_b64 s[8:9], 0x2000
	v_cvt_pk_bf16_f32 v147, v90, v91
	v_cvt_pk_bf16_f32 v146, v88, v89
	v_cvt_pk_bf16_f32 v153, v86, v87
	v_cvt_pk_bf16_f32 v152, v84, v85
	v_cvt_pk_bf16_f32 v151, v82, v83
	v_cvt_pk_bf16_f32 v150, v80, v81
	v_cvt_pk_bf16_f32 v157, v107, v109
	v_cvt_pk_bf16_f32 v156, v106, v108
	v_cvt_pk_bf16_f32 v155, v105, v177
	v_cvt_pk_bf16_f32 v154, v104, v176
	v_cvt_pk_bf16_f32 v161, v174, v175
	v_cvt_pk_bf16_f32 v160, v168, v169
	v_cvt_pk_bf16_f32 v159, v98, v99
	v_cvt_pk_bf16_f32 v158, v166, v167
	v_cvt_pk_bf16_f32 v148, v92, v93
	v_cvt_pk_bf16_f32 v149, v94, v95
	v_add_u32_e32 v80, s11, v197
	v_lshl_add_u64 v[184:185], v[184:185], 0, s[8:9]
	v_lshl_add_u64 v[190:191], v[190:191], 0, s[92:93]
	s_cmpk_eq_i32 s10, 0x80
	v_lshl_add_u64 v[192:193], v[192:193], 0, s[92:93]
	s_waitcnt vmcnt(0)
	ds_write_b128 v80, v[162:165] offset:26624
	s_waitcnt lgkmcnt(0)
	s_barrier
	s_cbranch_scc1 .LBB0_639
	global_load_dwordx4 v[166:169], v[190:191], off
	s_and_saveexec_b64 s[8:9], s[0:1]
	s_cbranch_execnz .LBB0_634
	s_branch .LBB0_635
